# fox dk staging: batch the strided CLOC loads (all issued before one wait)
# baseline (speedup 1.0000x reference)
.LBB0_663:
	s_mov_b64 s[8:9], exec
	s_mov_b64 s[12:13], 0x4000
	global_load_dword v98, v[2:3], off
	ds_read_b32 v106, v4
	v_add_u32_e32 v6, 0x200, v6
	v_cmp_gt_i32_e32 vcc, s11, v6
	v_lshl_add_u64 v[2:3], v[2:3], 0, s[12:13]
	v_add_u32_e32 v4, 16, v4
	s_nop 1
	s_and_b64 exec, exec, vcc
	s_cbranch_execz .Ldk_wait
	global_load_dword v99, v[2:3], off
	ds_read_b32 v107, v4
	v_add_u32_e32 v6, 0x200, v6
	v_cmp_gt_i32_e32 vcc, s11, v6
	v_lshl_add_u64 v[2:3], v[2:3], 0, s[12:13]
	v_add_u32_e32 v4, 16, v4
	s_nop 1
	s_and_b64 exec, exec, vcc
	s_cbranch_execz .Ldk_wait
	global_load_dword v100, v[2:3], off
	ds_read_b32 v108, v4
	v_add_u32_e32 v6, 0x200, v6
	v_cmp_gt_i32_e32 vcc, s11, v6
	v_lshl_add_u64 v[2:3], v[2:3], 0, s[12:13]
	v_add_u32_e32 v4, 16, v4
	s_nop 1
	s_and_b64 exec, exec, vcc
	s_cbranch_execz .Ldk_wait
	global_load_dword v101, v[2:3], off
	ds_read_b32 v109, v4
	v_add_u32_e32 v6, 0x200, v6
	v_cmp_gt_i32_e32 vcc, s11, v6
	v_lshl_add_u64 v[2:3], v[2:3], 0, s[12:13]
	v_add_u32_e32 v4, 16, v4
	s_nop 1
	s_and_b64 exec, exec, vcc
	s_cbranch_execz .Ldk_wait
	global_load_dword v102, v[2:3], off
	ds_read_b32 v110, v4
	v_add_u32_e32 v6, 0x200, v6
	v_cmp_gt_i32_e32 vcc, s11, v6
	v_lshl_add_u64 v[2:3], v[2:3], 0, s[12:13]
	v_add_u32_e32 v4, 16, v4
	s_nop 1
	s_and_b64 exec, exec, vcc
	s_cbranch_execz .Ldk_wait
	global_load_dword v103, v[2:3], off
	ds_read_b32 v111, v4
	v_add_u32_e32 v6, 0x200, v6
	v_cmp_gt_i32_e32 vcc, s11, v6
	v_lshl_add_u64 v[2:3], v[2:3], 0, s[12:13]
	v_add_u32_e32 v4, 16, v4
	s_nop 1
	s_and_b64 exec, exec, vcc
	s_cbranch_execz .Ldk_wait
	global_load_dword v104, v[2:3], off
	ds_read_b32 v112, v4
	v_add_u32_e32 v6, 0x200, v6
	v_cmp_gt_i32_e32 vcc, s11, v6
	v_lshl_add_u64 v[2:3], v[2:3], 0, s[12:13]
	v_add_u32_e32 v4, 16, v4
	s_nop 1
	s_and_b64 exec, exec, vcc
	s_cbranch_execz .Ldk_wait
	global_load_dword v105, v[2:3], off
	ds_read_b32 v113, v4
.Ldk_wait:
	s_mov_b64 exec, s[8:9]
	v_mov_b32_e32 v6, v0
	s_waitcnt vmcnt(0) lgkmcnt(0)
	v_add_f32_e32 v7, v106, v98
	v_mul_f32_e32 v7, 0xbfb8aa3b, v7
	ds_write_b32 v5, v7
	v_add_u32_e32 v6, 0x200, v6
	v_cmp_gt_i32_e32 vcc, s11, v6
	v_add_u32_e32 v5, 0x800, v5
	s_nop 1
	s_and_b64 exec, exec, vcc
	s_cbranch_execz .Ldk_done
	v_add_f32_e32 v7, v107, v99
	v_mul_f32_e32 v7, 0xbfb8aa3b, v7
	ds_write_b32 v5, v7
	v_add_u32_e32 v6, 0x200, v6
	v_cmp_gt_i32_e32 vcc, s11, v6
	v_add_u32_e32 v5, 0x800, v5
	s_nop 1
	s_and_b64 exec, exec, vcc
	s_cbranch_execz .Ldk_done
	v_add_f32_e32 v7, v108, v100
	v_mul_f32_e32 v7, 0xbfb8aa3b, v7
	ds_write_b32 v5, v7
	v_add_u32_e32 v6, 0x200, v6
	v_cmp_gt_i32_e32 vcc, s11, v6
	v_add_u32_e32 v5, 0x800, v5
	s_nop 1
	s_and_b64 exec, exec, vcc
	s_cbranch_execz .Ldk_done
	v_add_f32_e32 v7, v109, v101
	v_mul_f32_e32 v7, 0xbfb8aa3b, v7
	ds_write_b32 v5, v7
	v_add_u32_e32 v6, 0x200, v6
	v_cmp_gt_i32_e32 vcc, s11, v6
	v_add_u32_e32 v5, 0x800, v5
	s_nop 1
	s_and_b64 exec, exec, vcc
	s_cbranch_execz .Ldk_done
	v_add_f32_e32 v7, v110, v102
	v_mul_f32_e32 v7, 0xbfb8aa3b, v7
	ds_write_b32 v5, v7
	v_add_u32_e32 v6, 0x200, v6
	v_cmp_gt_i32_e32 vcc, s11, v6
	v_add_u32_e32 v5, 0x800, v5
	s_nop 1
	s_and_b64 exec, exec, vcc
	s_cbranch_execz .Ldk_done
	v_add_f32_e32 v7, v111, v103
	v_mul_f32_e32 v7, 0xbfb8aa3b, v7
	ds_write_b32 v5, v7
	v_add_u32_e32 v6, 0x200, v6
	v_cmp_gt_i32_e32 vcc, s11, v6
	v_add_u32_e32 v5, 0x800, v5
	s_nop 1
	s_and_b64 exec, exec, vcc
	s_cbranch_execz .Ldk_done
	v_add_f32_e32 v7, v112, v104
	v_mul_f32_e32 v7, 0xbfb8aa3b, v7
	ds_write_b32 v5, v7
	v_add_u32_e32 v6, 0x200, v6
	v_cmp_gt_i32_e32 vcc, s11, v6
	v_add_u32_e32 v5, 0x800, v5
	s_nop 1
	s_and_b64 exec, exec, vcc
	s_cbranch_execz .Ldk_done
	v_add_f32_e32 v7, v113, v105
	v_mul_f32_e32 v7, 0xbfb8aa3b, v7
	ds_write_b32 v5, v7
.Ldk_done:
.LBB0_664:
	s_or_b64 exec, exec, s[2:3]
	v_readlane_b32 s2, v253, 63
	s_sub_i32 s23, 0xf00, s58
	v_readlane_b32 s3, v252, 0
	v_add_u32_e32 v4, s23, v189
	s_lshl_b32 s14, s10, 7
	v_mov_b64_e32 v[2:3], s[2:3]
	s_movk_i32 s2, 0x1800
	v_mad_i64_i32 v[2:3], s[2:3], v4, s2, v[2:3]
	v_lshl_add_u64 v[2:3], v[2:3], 0, s[14:15]
	v_lshl_add_u64 v[2:3], v[2:3], 0, v[174:175]
	global_load_dwordx4 v[114:117], v[2:3], off
	global_load_dwordx4 v[106:109], v[2:3], off offset:32
	global_load_dwordx4 v[102:105], v[2:3], off offset:64
	global_load_dwordx4 v[98:101], v[2:3], off offset:96
	s_waitcnt vmcnt(0) lgkmcnt(0)
	s_barrier
	s_lshr_b32 s29, s11, 6
	v_cmp_le_u32_e32 vcc, s29, v190
	s_and_saveexec_b64 s[2:3], vcc
	s_xor_b64 s[2:3], exec, s[2:3]
	s_sub_i32 s11, 0, s58
	s_or_saveexec_b64 s[2:3], s[2:3]
	s_mov_b64 s[8:9], 0
	v_mov_b32_e32 v2, s11
	s_xor_b64 exec, exec, s[2:3]
	s_cbranch_execz .LBB0_668
	s_lshl_b32 s8, s58, 2
	s_sub_i32 s8, 0, s8
	v_mov_b32_e32 v2, s8
	ds_read_b32 v2, v2 offset:64512
	ds_read_b32 v3, v232 offset:49660
	s_mov_b32 s9, 0x43000000
	s_sub_i32 s8, 0, s58
	s_waitcnt lgkmcnt(0)
	v_sub_f32_e32 v2, v2, v3
	v_cmp_lt_f32_e32 vcc, s9, v2
	v_mov_b32_e32 v2, s8
	s_and_b64 s[8:9], vcc, exec
